# norm2 latent rows: all 16 loads of a row issued up front
# speedup vs baseline: 1.0043x; 1.0043x over previous
; __device__ __forceinline__ unsigned cvt_pk_bf16(float lo, float hi) { unsigned r; asm volatile("v_cvt_pk_bf16_f32 %0, %1, %2" : "=v"(r) : "v"(lo), "v"(hi)); return r; }
; template <int NP> __device__ __forceinline__ void mod_row(float* xrow, const float* prow, const float* g, const float* sh, const float* sc, bf16_t* orow, int lane) {
;     f32x4 v[4]; float s = 0.f;
; #pragma unroll
;     for (int j = 0; j < 4; ++j) { v[j] = *(const f32x4*)(xrow + 4 * lane + 256 * j);
;         if (NP > 0) {
; #pragma unroll
;             for (int q = 0; q < NP; ++q) v[j] = v[j] + *(const f32x4*)(prow + (size_t)q * MC * DM + 4 * lane + 256 * j);
;             *(f32x4*)(xrow + 4 * lane + 256 * j) = v[j]; }
;         s += (v[j].x * v[j].x + v[j].y * v[j].y) + (v[j].z * v[j].z + v[j].w * v[j].w); }
;     const float rstd = rsqrtf(wave_sum(s, lane) * (1.f / DM) + EPSV);
; #pragma unroll
;     for (int j = 0; j < 4; ++j) {
;         const int c = 4 * lane + 256 * j;
;         const f32x4 gg = *(const f32x4*)(g + c), ss = *(const f32x4*)(sc + c), hh = *(const f32x4*)(sh + c);
;         const f32x4 o = v[j] * rstd * gg * (ss + 1.0f) + hh;
;         u32x2 w; w.x = cvt_pk_bf16(o.x, o.y); w.y = cvt_pk_bf16(o.z, o.w);
;         *(u32x2*)(orow + c) = w;
;     }
; }
.LBB0_60:
	s_andn2_b64 vcc, exec, s[2:3]
	s_cbranch_vccnz .LBB0_57
	global_load_dwordx4 v[12:15], v[30:31], off offset:-2048
	global_load_dwordx4 v[8:11], v[30:31], off offset:-1024
	global_load_dwordx4 v[0:3], v[30:31], off
	global_load_dwordx4 v[4:7], v[30:31], off offset:1024
	s_ashr_i32 s17, s16, 31
	s_lshl_b64 s[2:3], s[16:17], 2
	s_add_u32 s2, s59, s2
	s_addc_u32 s3, s60, s3
	s_add_u32 s16, s2, 0x3000
	s_addc_u32 s17, s3, 0
	s_add_u32 s48, s2, 0x4000
	s_addc_u32 s49, s3, 0
	global_load_dwordx4 v[52:55], v[22:23], off
	global_load_dwordx4 v[56:59], v48, s[48:49]
	global_load_dwordx4 v[60:63], v48, s[16:17]
	global_load_dwordx4 v[64:67], v[22:23], off offset:1024
	global_load_dwordx4 v[68:71], v47, s[48:49]
	global_load_dwordx4 v[72:75], v47, s[16:17]
	global_load_dwordx4 v[76:79], v[22:23], off offset:2048
	global_load_dwordx4 v[80:83], v46, s[48:49]
	global_load_dwordx4 v[84:87], v46, s[16:17]
	global_load_dwordx4 v[88:91], v[22:23], off offset:3072
	global_load_dwordx4 v[92:95], v45, s[48:49]
	global_load_dwordx4 v[96:99], v45, s[16:17]
	v_lshl_add_u64 v[100:101], s[42:43], 0, v[180:181]
	s_waitcnt vmcnt(14)
	v_pk_mul_f32 v[36:37], v[14:15], v[14:15]
	v_pk_mul_f32 v[38:39], v[12:13], v[12:13]
	s_nop 0
	v_pk_mov_b32 v[40:41], v[38:39], v[36:37] op_sel:[1,0]
	v_mov_b32_e32 v39, v37
	v_pk_add_f32 v[32:33], v[40:41], v[38:39]
	v_pk_mul_f32 v[36:37], v[10:11], v[10:11]
	v_pk_mul_f32 v[38:39], v[8:9], v[8:9]
	v_pk_add_f32 v[32:33], v[32:33], v[32:33] op_sel:[0,1] op_sel_hi:[1,0]
	v_pk_mov_b32 v[40:41], v[38:39], v[36:37] op_sel:[1,0]
	v_mov_b32_e32 v39, v37
	v_pk_add_f32 v[34:35], v[40:41], v[38:39]
	s_nop 1
	v_pk_add_f32 v[34:35], v[34:35], v[34:35] op_sel:[0,1] op_sel_hi:[1,0]
	s_waitcnt vmcnt(12)
	v_mul_f32_e32 v36, v4, v4
	v_mul_f32_e32 v37, v5, v5
	v_mov_b32_e32 v33, v36
	v_mov_b32_e32 v35, v37
	v_pk_add_f32 v[32:33], v[32:33], v[34:35]
	v_mul_f32_e32 v34, v1, v1
	v_mul_f32_e32 v36, v3, v3
	v_mul_f32_e32 v38, v6, v6
	v_mul_f32_e32 v39, v7, v7
	v_pk_fma_f32 v[34:35], v[0:1], v[0:1], v[34:35] op_sel_hi:[1,1,0]
	v_pk_fma_f32 v[36:37], v[2:3], v[2:3], v[36:37] op_sel_hi:[1,1,0]
	v_mov_b32_e32 v35, v38
	v_mov_b32_e32 v37, v39
	v_pk_add_f32 v[34:35], v[34:35], v[36:37]
	s_nop 0
	v_pk_add_f32 v[32:33], v[32:33], v[34:35]
	s_nop 1
	v_add_f32_e32 v32, v32, v33
	ds_bpermute_b32 v33, v17, v32
	s_waitcnt lgkmcnt(0)
	v_add_f32_e32 v32, v32, v33
	ds_bpermute_b32 v33, v25, v32
	s_waitcnt lgkmcnt(0)
	v_add_f32_e32 v32, v32, v33
	ds_bpermute_b32 v33, v27, v32
	s_waitcnt lgkmcnt(0)
	v_add_f32_e32 v32, v32, v33
	ds_bpermute_b32 v33, v29, v32
	s_waitcnt lgkmcnt(0)
	v_add_f32_e32 v32, v32, v33
	ds_bpermute_b32 v33, v42, v32
	s_waitcnt lgkmcnt(0)
	v_add_f32_e32 v32, v32, v33
	ds_bpermute_b32 v33, v43, v32
	s_waitcnt lgkmcnt(0)
	v_add_f32_e32 v32, v32, v33
	v_fmamk_f32 v32, v32, 0x3a800000, v195
	v_cmp_gt_f32_e32 vcc, s15, v32
	v_mul_f32_e32 v33, 0x4b800000, v32
	s_nop 0
	v_cndmask_b32_e32 v32, v32, v33, vcc
	v_rsq_f32_e32 v32, v32
	s_nop 0
	v_mul_f32_e32 v33, 0x45800000, v32
	v_cndmask_b32_e32 v32, v32, v33, vcc
	v_pk_mul_f32 v[14:15], v[14:15], v[32:33] op_sel_hi:[1,0]
	v_pk_mul_f32 v[12:13], v[12:13], v[32:33] op_sel_hi:[1,0]
	v_pk_mul_f32 v[10:11], v[10:11], v[32:33] op_sel_hi:[1,0]
	v_pk_mul_f32 v[8:9], v[8:9], v[32:33] op_sel_hi:[1,0]
	v_pk_mul_f32 v[2:3], v[2:3], v[32:33] op_sel_hi:[1,0]
	v_pk_mul_f32 v[0:1], v[0:1], v[32:33] op_sel_hi:[1,0]
	v_pk_mul_f32 v[6:7], v[6:7], v[32:33] op_sel_hi:[1,0]
	v_pk_mul_f32 v[4:5], v[4:5], v[32:33] op_sel_hi:[1,0]
	s_waitcnt vmcnt(9)
	v_pk_mul_f32 v[12:13], v[52:53], v[12:13]
	v_pk_mul_f32 v[14:15], v[54:55], v[14:15]
	v_pk_add_f32 v[36:37], v[56:57], 1.0 op_sel_hi:[1,0]
	v_pk_add_f32 v[34:35], v[58:59], 1.0 op_sel_hi:[1,0]
	v_pk_fma_f32 v[12:13], v[36:37], v[12:13], v[60:61]
	s_nop 0
	v_pk_fma_f32 v[14:15], v[34:35], v[14:15], v[62:63]
	v_cvt_pk_bf16_f32 v12, v12, v13
	s_nop 0
	v_cvt_pk_bf16_f32 v13, v14, v15
	global_store_dwordx2 v[100:101], v[12:13], off
	s_waitcnt vmcnt(7)
	v_pk_mul_f32 v[8:9], v[64:65], v[8:9]
	v_pk_mul_f32 v[10:11], v[66:67], v[10:11]
	v_pk_add_f32 v[36:37], v[68:69], 1.0 op_sel_hi:[1,0]
	v_pk_add_f32 v[34:35], v[70:71], 1.0 op_sel_hi:[1,0]
	v_pk_fma_f32 v[8:9], v[36:37], v[8:9], v[72:73]
	v_pk_fma_f32 v[10:11], v[34:35], v[10:11], v[74:75]
	v_cvt_pk_bf16_f32 v8, v8, v9
	s_nop 0
	v_cvt_pk_bf16_f32 v9, v10, v11
	global_store_dwordx2 v[100:101], v[8:9], off offset:512
	s_waitcnt vmcnt(5)
	v_pk_mul_f32 v[0:1], v[76:77], v[0:1]
	v_pk_mul_f32 v[2:3], v[78:79], v[2:3]
	v_pk_add_f32 v[36:37], v[80:81], 1.0 op_sel_hi:[1,0]
	v_pk_add_f32 v[34:35], v[82:83], 1.0 op_sel_hi:[1,0]
	v_pk_fma_f32 v[0:1], v[36:37], v[0:1], v[84:85]
	v_pk_fma_f32 v[2:3], v[34:35], v[2:3], v[86:87]
	v_cvt_pk_bf16_f32 v102, v0, v1
	s_nop 0
	v_cvt_pk_bf16_f32 v103, v2, v3
	global_store_dwordx2 v[100:101], v[102:103], off offset:1024
	s_mov_b64 s[48:49], s[42:43]
	s_waitcnt vmcnt(3)
	v_pk_mul_f32 v[0:1], v[4:5], v[88:89]
	v_pk_mul_f32 v[2:3], v[6:7], v[90:91]
	v_pk_add_f32 v[6:7], v[92:93], 1.0 op_sel_hi:[1,0]
	v_pk_add_f32 v[4:5], v[94:95], 1.0 op_sel_hi:[1,0]
	v_pk_fma_f32 v[0:1], v[0:1], v[6:7], v[96:97]
	v_pk_fma_f32 v[2:3], v[2:3], v[4:5], v[98:99]
	v_cvt_pk_bf16_f32 v0, v0, v1
	s_nop 0
	v_cvt_pk_bf16_f32 v1, v2, v3
	s_branch .LBB0_57

